# adds seam P1-P2 XCD-local: P1 row loop remapped to the XCD that consumes the rows (rotated trip order per XCD), one L2 writeback per XCD in the first P2 epilogue for P1 outputs consumed by other XCDs
# speedup vs baseline: 1.0186x; 1.0054x over previous
.LBB0_123:
	s_lshl_b32 s12, s25, 3
	s_mov_b64 s[92:93], s[20:21]
	s_mov_b32 s94, s12
	v_and_b32_e32 v1, 32, v0
	s_cmpk_gt_i32 s20, 0x7fff
	v_cmp_eq_u32_e64 s[2:3], 0, v1
	v_cmp_eq_u32_e64 s[4:5], 0, v26
	s_cbranch_scc1 .LBB0_132
	s_mov_b32 s90, 0
	s_lshl_b32 s0, s25, 4
	s_cmp_eq_u32 s25, 0x100
	s_cbranch_scc0 .Lp1_noremap
	s_mov_b32 s90, 1
	s_mov_b32 s91, 0
	s_lshr_b32 s97, s20, 8
	s_and_b32 s20, s20, 0xff
	s_lshl_b32 s0, s97, 12
	s_add_i32 s96, s20, s0
	s_lshl_b32 s0, s97, 9
	s_add_i32 s20, s96, s0
	s_mov_b32 s21, 0
	s_movk_i32 s12, 0x100
	s_movk_i32 s0, 0x200
.Lp1_noremap:
	s_lshl_b64 s[16:17], s[20:21], 2
	v_lshlrev_b32_e32 v32, 2, v26
	s_add_u32 s13, s16, 0x280000
	v_ashrrev_i32_e32 v33, 31, v32
	s_addc_u32 s16, s17, 0
	s_lshl_b64 s[34:35], s[20:21], 10
	v_lshl_add_u64 v[36:37], s[34:35], 0, v[32:33]
	s_add_i32 s34, s20, s12
	s_ashr_i32 s35, s34, 31
	s_ashr_i32 s1, s0, 31
	s_lshl_b64 s[50:51], s[34:35], 10
	s_lshl_b64 s[44:45], s[0:1], 2
	s_lshl_b64 s[48:49], s[0:1], 10
	v_lshl_add_u64 v[38:39], s[50:51], 0, v[32:33]
	s_lshl_b64 s[50:51], s[20:21], 12
	s_add_u32 s50, s68, s50
	v_lshlrev_b64 v[10:11], 4, v[26:27]
	s_addc_u32 s51, s69, s51
	v_lshl_add_u64 v[30:31], s[68:69], 0, v[10:11]
	v_lshl_add_u64 v[10:11], s[50:51], 0, v[10:11]
	s_mov_b64 s[50:51], 0x800
	v_lshl_add_u64 v[40:41], v[10:11], 0, s[50:51]
	s_lshl_b64 s[50:51], s[0:1], 12
	s_lshl_b64 s[34:35], s[34:35], 2
	v_mov_b32_e32 v12, s76
	v_mov_b32_e32 v13, s77
	s_add_u32 s1, s34, 0x280000
	v_lshl_add_u64 v[34:35], v[32:33], 2, v[12:13]
	v_lshl_add_u32 v1, v26, 4, 0
	s_addc_u32 s17, s35, 0
	v_mov_b32_e32 v27, 0x358637bd
	s_mov_b32 s33, 0x800000
	s_mov_b64 s[52:53], 0x1000
	s_movk_i32 s56, 0x1000
	s_mov_b32 s57, 0x42fe0000
	s_movk_i32 s58, 0xff81
	v_mov_b32_e32 v29, 0x7f
	s_mov_b32 s59, 0x40c0c00
	s_mov_b32 s60, 0x3000000
	v_mov_b32_e32 v42, 0
	s_mov_b32 s61, s20
	s_branch .LBB0_127

.LBB0_126:
	s_cmp_eq_u32 s90, 1
	s_cbranch_scc0 .Lp1_lin
	s_add_i32 s91, s91, 1
	s_cmp_ge_u32 s91, 8
	s_cbranch_scc1 .LBB0_132
	s_add_i32 s61, s91, s97
	s_and_b32 s61, s61, 7
	s_lshl_b32 s61, s61, 9
	s_add_i32 s61, s61, s96
	s_lshl_b32 s13, s61, 2
	s_add_u32 s13, s13, 0x280000
	s_mov_b32 s16, 0
	s_add_i32 s34, s61, 0x100
	s_lshl_b32 s1, s34, 2
	s_add_u32 s1, s1, 0x280000
	s_mov_b32 s17, 0
	s_lshl_b32 s34, s61, 10
	s_mov_b32 s35, 0
	v_lshl_add_u64 v[36:37], s[34:35], 0, v[32:33]
	s_add_u32 s34, s34, 0x40000
	v_lshl_add_u64 v[38:39], s[34:35], 0, v[32:33]
	s_lshl_b32 s34, s61, 12
	s_add_u32 s34, s34, 0x800
	v_lshl_add_u64 v[40:41], v[30:31], 0, s[34:35]
	s_branch .LBB0_127

.LBB0_132:
	s_mov_b64 s[20:21], s[92:93]
	s_mov_b32 s12, s94
	s_cmp_lt_i32 s20, 8
	v_readlane_b32 s88, v254, 57
	s_cbranch_scc0 .LBB0_146
	s_movk_i32 s0, 0x400
	v_cmp_gt_i32_e32 vcc, s0, v26
	s_waitcnt vmcnt(4)
	v_mov_b32_e32 v13, 0
	s_and_saveexec_b64 s[44:45], vcc
	s_cbranch_execz .LBB0_143
	v_max_i32_e32 v1, 0x3c0, v26
	v_sub_u32_e32 v1, v1, v26
	v_add_u32_e32 v1, 63, v1
	s_mul_hi_i32 s13, s20, 0xb000
	s_mul_i32 s16, s20, 0xb000
	v_cmp_lt_u32_e32 vcc, 63, v1
	s_mov_b64 s[34:35], -1
	v_mov_b32_e32 v13, 0
	v_mov_b32_e32 v10, v26
	s_and_saveexec_b64 s[48:49], vcc
	s_cbranch_execz .LBB0_138
	s_add_u32 s0, s40, s16
	v_lshrrev_b32_e32 v1, 6, v1
	s_addc_u32 s1, s41, s13
	v_add_u32_e32 v1, 1, v1
	s_add_u32 s10, s0, 0x6000
	v_add_u32_e32 v27, 64, v26
	s_addc_u32 s11, s1, 0
	v_and_b32_e32 v12, 0x7fffffe, v1
	v_mov_b32_e32 v15, 0
	s_mov_b32 s17, 2
	s_mov_b64 s[50:51], 0
	v_mov_b64_e32 v[10:11], v[26:27]
	v_mov_b32_e32 v16, 0

.LBB0_170:
	s_cmp_gt_i32 s31, 2
	s_cselect_b64 s[0:1], -1, 0
	s_and_b64 s[2:3], s[14:15], s[0:1]
	s_andn2_b64 vcc, exec, s[2:3]
	s_cbranch_vccnz .LBB0_204
	s_waitcnt vmcnt(0)
	v_cmp_eq_u32_e32 vcc, 0, v0
	s_barrier
	v_mov_b32_e32 v1, s88
	ds_read_b32 v2, v1 offset:8
	s_waitcnt lgkmcnt(0)
	v_readfirstlane_b32 s98, v2
	s_cmp_eq_u32 s98, 1
	s_cbranch_scc1 .Llb_loc_s1
	s_and_saveexec_b64 s[2:3], vcc
	s_cbranch_execz .LBB0_203
	v_mov_b32_e32 v1, s88
	s_waitcnt vmcnt(0) expcnt(0) lgkmcnt(0)
	ds_read_b32 v2, v1
	ds_read_b32 v1, v1 offset:4
	s_waitcnt lgkmcnt(1)
	v_cmp_ne_u32_e32 vcc, 0, v2
	s_cbranch_vccnz .LBB0_187
	v_readlane_b32 s4, v254, 8
	v_readlane_b32 s5, v254, 9
	s_load_dwordx2 s[12:13], s[4:5], 0x4
	s_add_u32 s4, s28, 0x4200
	s_addc_u32 s5, s29, 0
	s_add_u32 s10, s28, 0x4400
	s_addc_u32 s11, s29, 0
	s_waitcnt lgkmcnt(0)
	s_mul_i32 s16, s12, s25
	s_add_u32 s12, s28, 0x4500
	s_mul_i32 s16, s16, s13
	s_addc_u32 s13, s29, 0
	s_add_u32 s14, s28, 0x4600
	s_addc_u32 s15, s29, 0
	s_add_u32 s20, s28, 0x4700
	s_addc_u32 s21, s29, 0
	s_add_u32 s22, s28, 0x4800
	s_addc_u32 s23, s29, 0
	s_add_u32 s38, s28, 0x4900
	s_addc_u32 s39, s29, 0
	s_add_u32 s44, s28, 0x4a00
	s_addc_u32 s45, s29, 0
	s_add_u32 s48, s28, 0x4b00
	s_addc_u32 s49, s29, 0
	s_add_u32 s50, s28, 0x4c00
	s_addc_u32 s51, s29, 0
	s_add_u32 s52, s28, 0x4d00
	s_addc_u32 s53, s29, 0
	s_add_u32 s66, s28, 0x4e00
	s_addc_u32 s67, s29, 0
	s_add_u32 s70, s28, 0x4f00
	s_addc_u32 s71, s29, 0
	s_add_u32 s72, s28, 0x5000
	s_addc_u32 s73, s29, 0
	s_add_u32 s74, s28, 0x5100
	s_addc_u32 s75, s29, 0
	s_add_u32 s76, s28, 0x5200
	s_addc_u32 s77, s29, 0
	s_add_u32 s78, s28, 0x5300
	s_addc_u32 s79, s29, 0
	s_mov_b32 s17, 1
	v_mov_b32_e32 v17, 0
	s_branch .LBB0_175

.Llb_loc_s1:
	s_and_saveexec_b64 s[2:3], vcc
	s_cbranch_execz .Llb_done_s1
	v_mov_b32_e32 v1, s88
	ds_read_b32 v2, v1
	v_readlane_b32 s4, v254, 14
	v_readlane_b32 s10, v254, 12
	v_readlane_b32 s11, v254, 13
	s_lshl_b32 s4, s4, 8
	s_add_u32 s4, s10, s4
	s_addc_u32 s5, s11, 0
	v_mov_b32_e32 v3, 0x2400
	v_mov_b32_e32 v4, 1
	global_atomic_add v3, v4, s[4:5]
	s_waitcnt lgkmcnt(0)
	v_mul_lo_u32 v2, v2, 1
	s_mov_b32 s99, 0

.LBB0_217:
	v_mbcnt_lo_u32_b32 v70, -1, 0
	v_mbcnt_hi_u32_b32 v70, -1, v70
	s_lshl_b32 s34, s88, 8
	v_ashrrev_i32_e32 v71, 1, v70
	v_and_or_b32 v66, v70, 15, s61
	s_or_b32 s34, s34, s38
	v_and_b32_e32 v68, -8, v71
	v_lshl_add_u32 v66, s82, 8, v66
	v_add_u32_e32 v68, s34, v68
	v_ashrrev_i32_e32 v67, 31, v66
	v_ashrrev_i32_e32 v69, 31, v68
	v_and_or_b32 v169, v70, 16, v66
	v_and_b32_e32 v150, 16, v71
	v_lshl_add_u64 v[66:67], v[66:67], 2, s[44:45]
	v_lshl_add_u64 v[70:71], v[68:69], 2, s[36:37]
	global_load_dword v174, v[66:67], off
	global_load_dword v172, v[66:67], off offset:64
	global_load_dword v170, v[66:67], off offset:128
	global_load_dword v168, v[66:67], off offset:192
	global_load_dword v166, v[66:67], off offset:512
	global_load_dword v164, v[66:67], off offset:576
	global_load_dword v162, v[66:67], off offset:640
	global_load_dword v160, v[66:67], off offset:704
	global_load_dwordx4 v[74:77], v[70:71], off offset:16
	global_load_dwordx4 v[78:81], v[70:71], off
	s_nop 0
	global_load_dwordx4 v[66:69], v[70:71], off offset:528
	s_nop 0
	global_load_dwordx4 v[70:73], v[70:71], off offset:512
	v_cvt_f32_i32_e32 v145, v145
	v_cvt_f32_i32_e32 v144, v144
	s_lshl_b32 s34, s88, 7
	v_mov_b64_e32 v[158:159], s[20:21]
	s_movk_i32 s75, 0xb00
	v_cvt_f32_i32_e32 v143, v143
	v_cvt_f32_i32_e32 v142, v142
	s_ashr_i32 s35, s34, 31
	v_mad_i64_i32 v[158:159], s[84:85], v169, s75, v[158:159]
	v_cvt_f32_i32_e32 v139, v139
	v_cvt_f32_i32_e32 v138, v138
	v_lshl_add_u64 v[158:159], v[158:159], 0, s[34:35]
	v_cvt_f32_i32_e32 v135, v135
	v_cvt_f32_i32_e32 v134, v134
	v_lshl_add_u64 v[158:159], v[158:159], 0, s[38:39]
	v_lshl_add_u64 v[158:159], v[158:159], 0, v[150:151]
	v_cvt_f32_i32_e32 v137, v137
	v_cvt_f32_i32_e32 v136, v136
	v_cvt_f32_i32_e32 v131, v131
	v_cvt_f32_i32_e32 v130, v130
	v_cvt_f32_i32_e32 v129, v129
	v_cvt_f32_i32_e32 v128, v128
	v_cvt_f32_i32_e32 v125, v125
	v_cvt_f32_i32_e32 v124, v124
	v_cvt_f32_i32_e32 v127, v127
	v_cvt_f32_i32_e32 v126, v126
	v_cvt_f32_i32_e32 v121, v121
	v_cvt_f32_i32_e32 v120, v120
	v_cvt_f32_i32_e32 v123, v123
	v_cvt_f32_i32_e32 v122, v122
	v_cvt_f32_i32_e32 v117, v117
	v_cvt_f32_i32_e32 v116, v116
	v_cvt_f32_i32_e32 v115, v115
	v_cvt_f32_i32_e32 v114, v114
	v_cvt_f32_i32_e32 v119, v119
	v_cvt_f32_i32_e32 v118, v118
	v_cvt_f32_i32_e32 v113, v113
	v_cvt_f32_i32_e32 v112, v112
	v_cvt_f32_i32_e32 v111, v111
	v_cvt_f32_i32_e32 v110, v110
	v_cvt_f32_i32_e32 v109, v109
	v_cvt_f32_i32_e32 v108, v108
	v_cvt_f32_i32_e32 v107, v107
	v_cvt_f32_i32_e32 v106, v106
	v_cvt_f32_i32_e32 v105, v105
	v_cvt_f32_i32_e32 v104, v104
	v_cvt_f32_i32_e32 v101, v101
	v_cvt_f32_i32_e32 v100, v100
	v_cvt_f32_i32_e32 v99, v99
	v_cvt_f32_i32_e32 v98, v98
	v_cvt_f32_i32_e32 v103, v103
	v_cvt_f32_i32_e32 v102, v102
	v_cvt_f32_i32_e32 v97, v97
	v_cvt_f32_i32_e32 v96, v96
	v_cvt_f32_i32_e32 v93, v93
	v_cvt_f32_i32_e32 v92, v92
	v_cvt_f32_i32_e32 v95, v95
	v_cvt_f32_i32_e32 v94, v94
	v_cvt_f32_i32_e32 v89, v89
	v_cvt_f32_i32_e32 v88, v88
	v_cvt_f32_i32_e32 v91, v91
	v_cvt_f32_i32_e32 v90, v90
	v_cvt_f32_i32_e32 v85, v85
	v_cvt_f32_i32_e32 v84, v84
	v_cvt_f32_i32_e32 v83, v83
	v_cvt_f32_i32_e32 v82, v82
	v_cvt_f32_i32_e32 v87, v87
	v_cvt_f32_i32_e32 v86, v86
	v_cvt_f32_i32_e32 v65, v65
	v_cvt_f32_i32_e32 v64, v64
	s_waitcnt vmcnt(0)
	s_cmp_lt_u32 s24, 8
	s_cbranch_scc0 .Lp2_nowb
	s_cmp_eq_u32 s83, 1
	s_cbranch_scc0 .Lp2_nowb
	v_readfirstlane_b32 s98, v0
	s_cmp_lt_u32 s98, 64
	s_cbranch_scc0 .Lp2_nowb
	buffer_wbl2 sc1
.Lp2_nowb:
	v_mul_f32_e32 v150, 0x41000000, v174
	s_mov_b32 s34, 0x16000
	v_cvt_f32_i32_e32 v63, v63
	v_cvt_f32_i32_e32 v62, v62
	v_cvt_f32_i32_e32 v61, v61
	v_cvt_f32_i32_e32 v60, v60
	v_pk_mul_f32 v[176:177], v[174:175], v[80:81] op_sel_hi:[0,1]
	v_pk_mul_f32 v[144:145], v[176:177], v[144:145]
	v_cvt_f32_i32_e32 v177, v141
	v_cvt_f32_i32_e32 v176, v140
	v_pk_mul_f32 v[178:179], v[174:175], v[78:79] op_sel_hi:[0,1]
	v_pk_mul_f32 v[142:143], v[178:179], v[142:143]
	v_pk_mul_f32 v[178:179], v[174:175], v[76:77] op_sel_hi:[0,1]
	v_pk_mul_f32 v[140:141], v[174:175], v[74:75] op_sel_hi:[0,1]
	v_pk_mul_f32 v[140:141], v[140:141], v[138:139]
	v_pk_mul_f32 v[138:139], v[178:179], v[176:177]
	v_pk_mul_f32 v[176:177], v[150:151], v[70:71] op_sel_hi:[0,1]
	v_pk_mul_f32 v[176:177], v[176:177], v[134:135]
	v_cvt_f32_i32_e32 v135, v133
	v_cvt_f32_i32_e32 v134, v132
	v_pk_mul_f32 v[174:175], v[150:151], v[72:73] op_sel_hi:[0,1]
	v_pk_mul_f32 v[136:137], v[174:175], v[136:137]
	v_pk_mul_f32 v[174:175], v[150:151], v[68:69] op_sel_hi:[0,1]
	v_pk_mul_f32 v[132:133], v[150:151], v[66:67] op_sel_hi:[0,1]
	v_pk_mul_f32 v[132:133], v[132:133], v[130:131]
	v_pk_mul_f32 v[134:135], v[174:175], v[134:135]
	v_pk_mul_f32 v[130:131], v[144:145], s[72:73] op_sel_hi:[1,0]
	v_pk_mul_f32 v[174:175], v[142:143], s[72:73] op_sel_hi:[1,0]
	v_exp_f32_e32 v130, v130
	v_exp_f32_e32 v174, v174
	v_exp_f32_e32 v175, v175
	v_exp_f32_e32 v131, v131
	v_cvt_f32_i32_e32 v59, v59
	v_cvt_f32_i32_e32 v58, v58
	v_pk_add_f32 v[174:175], v[174:175], 1.0 op_sel_hi:[1,0]
	v_pk_add_f32 v[130:131], v[130:131], 1.0 op_sel_hi:[1,0]
	v_rcp_f32_e32 v174, v174
	v_rcp_f32_e32 v175, v175
	v_rcp_f32_e32 v130, v130
	v_rcp_f32_e32 v131, v131
	v_cvt_f32_i32_e32 v57, v57
	v_pk_mul_f32 v[142:143], v[142:143], v[174:175]
	v_cvt_f32_i32_e32 v56, v56
	v_pk_mul_f32 v[130:131], v[144:145], v[130:131]
	v_cvt_f32_i32_e32 v53, v53
	v_pk_mul_f32 v[136:137], v[136:137], v[130:131]
	v_pk_mul_f32 v[130:131], v[176:177], v[142:143]
	v_cvt_f32_i32_e32 v52, v52
	v_med3_f32 v142, v130, s73, v167
	v_med3_f32 v131, v131, s73, v167
	v_mov_b32_e32 v130, v151
	v_cvt_pk_fp8_f32 v130, v142, v131
	v_pk_mul_f32 v[142:143], v[140:141], s[72:73] op_sel_hi:[1,0]
	v_med3_f32 v131, v136, s73, v167
	v_exp_f32_e32 v142, v142
	v_exp_f32_e32 v143, v143
	v_med3_f32 v136, v137, s73, v167
	v_cvt_pk_fp8_f32 v130, v131, v136 op_sel:[0,0,1]
	v_pk_mul_f32 v[136:137], v[138:139], s[72:73] op_sel_hi:[1,0]
	v_pk_add_f32 v[142:143], v[142:143], 1.0 op_sel_hi:[1,0]
	v_exp_f32_e32 v136, v136
	v_exp_f32_e32 v137, v137
	v_rcp_f32_e32 v142, v142
	v_rcp_f32_e32 v143, v143
	v_mov_b32_e32 v131, v151
	v_pk_add_f32 v[136:137], v[136:137], 1.0 op_sel_hi:[1,0]
	v_cvt_f32_i32_e32 v51, v51
	v_rcp_f32_e32 v136, v136
	v_rcp_f32_e32 v137, v137
	v_pk_mul_f32 v[140:141], v[140:141], v[142:143]
	v_cvt_f32_i32_e32 v50, v50
	v_pk_mul_f32 v[132:133], v[132:133], v[140:141]
	v_pk_mul_f32 v[136:137], v[138:139], v[136:137]
	v_med3_f32 v132, v132, s73, v167
	v_med3_f32 v133, v133, s73, v167
	v_cvt_pk_fp8_f32 v131, v132, v133
	v_pk_mul_f32 v[134:135], v[134:135], v[136:137]
	v_pk_mul_f32 v[136:137], v[172:173], v[78:79] op_sel_hi:[0,1]
	v_med3_f32 v132, v134, s73, v167
	v_med3_f32 v133, v135, s73, v167
	v_pk_mul_f32 v[134:135], v[172:173], v[80:81] op_sel_hi:[0,1]
	v_cvt_pk_fp8_f32 v131, v132, v133 op_sel:[0,0,1]
	v_mul_f32_e32 v132, 0x41000000, v172
	v_pk_mul_f32 v[128:129], v[134:135], v[128:129]
	v_pk_mul_f32 v[134:135], v[172:173], v[76:77] op_sel_hi:[0,1]
	v_pk_mul_f32 v[124:125], v[134:135], v[124:125]
	v_pk_mul_f32 v[134:135], v[132:133], v[72:73] op_sel_hi:[0,1]
	v_pk_mul_f32 v[126:127], v[136:137], v[126:127]
	v_pk_mul_f32 v[136:137], v[172:173], v[74:75] op_sel_hi:[0,1]
	v_pk_mul_f32 v[120:121], v[134:135], v[120:121]
	v_pk_mul_f32 v[134:135], v[132:133], v[68:69] op_sel_hi:[0,1]
	v_pk_mul_f32 v[122:123], v[136:137], v[122:123]
	v_pk_mul_f32 v[136:137], v[132:133], v[70:71] op_sel_hi:[0,1]
	v_pk_mul_f32 v[132:133], v[132:133], v[66:67] op_sel_hi:[0,1]
	v_pk_mul_f32 v[116:117], v[134:135], v[116:117]
	v_pk_mul_f32 v[134:135], v[126:127], s[72:73] op_sel_hi:[1,0]
	v_pk_mul_f32 v[114:115], v[132:133], v[114:115]
	v_pk_mul_f32 v[132:133], v[128:129], s[72:73] op_sel_hi:[1,0]
	v_exp_f32_e32 v134, v134
	v_exp_f32_e32 v135, v135
	v_exp_f32_e32 v132, v132
	v_exp_f32_e32 v133, v133
	v_pk_mul_f32 v[118:119], v[136:137], v[118:119]
	v_pk_add_f32 v[134:135], v[134:135], 1.0 op_sel_hi:[1,0]
	v_cvt_f32_i32_e32 v55, v55
	v_pk_add_f32 v[132:133], v[132:133], 1.0 op_sel_hi:[1,0]
	v_rcp_f32_e32 v134, v134
	v_rcp_f32_e32 v135, v135
	v_rcp_f32_e32 v132, v132
	v_rcp_f32_e32 v133, v133
	v_cvt_f32_i32_e32 v54, v54
	v_pk_mul_f32 v[126:127], v[126:127], v[134:135]
	v_cvt_f32_i32_e32 v49, v49
	v_pk_mul_f32 v[128:129], v[128:129], v[132:133]
	v_pk_mul_f32 v[118:119], v[118:119], v[126:127]
	v_pk_mul_f32 v[120:121], v[120:121], v[128:129]
	v_med3_f32 v118, v118, s73, v167
	v_med3_f32 v119, v119, s73, v167
	v_mov_b32_e32 v132, v151
	v_cvt_pk_fp8_f32 v132, v118, v119
	v_med3_f32 v118, v120, s73, v167
	v_med3_f32 v119, v121, s73, v167
	v_pk_mul_f32 v[120:121], v[122:123], s[72:73] op_sel_hi:[1,0]
	v_cvt_pk_fp8_f32 v132, v118, v119 op_sel:[0,0,1]
	v_exp_f32_e32 v120, v120
	v_exp_f32_e32 v121, v121
	v_pk_mul_f32 v[118:119], v[124:125], s[72:73] op_sel_hi:[1,0]
	v_mov_b32_e32 v133, v151
	v_exp_f32_e32 v118, v118
	v_exp_f32_e32 v119, v119
	v_pk_add_f32 v[120:121], v[120:121], 1.0 op_sel_hi:[1,0]
	v_cvt_f32_i32_e32 v48, v48
	v_rcp_f32_e32 v120, v120
	v_rcp_f32_e32 v121, v121
	v_pk_add_f32 v[118:119], v[118:119], 1.0 op_sel_hi:[1,0]
	v_cvt_f32_i32_e32 v45, v45
	v_rcp_f32_e32 v118, v118
	v_rcp_f32_e32 v119, v119
	v_pk_mul_f32 v[120:121], v[122:123], v[120:121]
	v_cvt_f32_i32_e32 v44, v44
	v_pk_mul_f32 v[114:115], v[114:115], v[120:121]
	v_pk_mul_f32 v[118:119], v[124:125], v[118:119]
	v_med3_f32 v114, v114, s73, v167
	v_med3_f32 v115, v115, s73, v167
	v_cvt_pk_fp8_f32 v133, v114, v115
	v_pk_mul_f32 v[116:117], v[116:117], v[118:119]
	v_pk_mul_f32 v[118:119], v[170:171], v[78:79] op_sel_hi:[0,1]
	v_med3_f32 v114, v116, s73, v167
	v_med3_f32 v115, v117, s73, v167
	v_pk_mul_f32 v[116:117], v[170:171], v[80:81] op_sel_hi:[0,1]
	v_cvt_pk_fp8_f32 v133, v114, v115 op_sel:[0,0,1]
	v_mul_f32_e32 v114, 0x41000000, v170
	v_pk_mul_f32 v[112:113], v[116:117], v[112:113]
	v_pk_mul_f32 v[116:117], v[170:171], v[76:77] op_sel_hi:[0,1]
	v_pk_mul_f32 v[110:111], v[118:119], v[110:111]
	v_pk_mul_f32 v[118:119], v[170:171], v[74:75] op_sel_hi:[0,1]
	v_pk_mul_f32 v[108:109], v[116:117], v[108:109]
	v_pk_mul_f32 v[116:117], v[114:115], v[72:73] op_sel_hi:[0,1]
	v_pk_mul_f32 v[106:107], v[118:119], v[106:107]
	v_pk_mul_f32 v[118:119], v[114:115], v[70:71] op_sel_hi:[0,1]
	v_pk_mul_f32 v[104:105], v[116:117], v[104:105]
	v_pk_mul_f32 v[116:117], v[114:115], v[68:69] op_sel_hi:[0,1]
	v_pk_mul_f32 v[114:115], v[114:115], v[66:67] op_sel_hi:[0,1]
	v_pk_mul_f32 v[114:115], v[114:115], v[98:99]
	v_pk_mul_f32 v[100:101], v[116:117], v[100:101]
	v_pk_mul_f32 v[98:99], v[112:113], s[72:73] op_sel_hi:[1,0]
	v_pk_mul_f32 v[116:117], v[110:111], s[72:73] op_sel_hi:[1,0]
	v_exp_f32_e32 v98, v98
	v_exp_f32_e32 v116, v116
	v_exp_f32_e32 v117, v117
	v_exp_f32_e32 v99, v99
	v_pk_mul_f32 v[102:103], v[118:119], v[102:103]
	v_cvt_f32_i32_e32 v47, v47
	v_pk_add_f32 v[116:117], v[116:117], 1.0 op_sel_hi:[1,0]
	v_pk_add_f32 v[98:99], v[98:99], 1.0 op_sel_hi:[1,0]
	v_rcp_f32_e32 v116, v116
	v_rcp_f32_e32 v117, v117
	v_rcp_f32_e32 v98, v98
	v_rcp_f32_e32 v99, v99
	v_cvt_f32_i32_e32 v46, v46
	v_pk_mul_f32 v[110:111], v[110:111], v[116:117]
	v_cvt_f32_i32_e32 v41, v41
	v_pk_mul_f32 v[98:99], v[112:113], v[98:99]
	v_cvt_f32_i32_e32 v40, v40
	v_pk_mul_f32 v[104:105], v[104:105], v[98:99]
	v_pk_mul_f32 v[98:99], v[102:103], v[110:111]
	v_cvt_f32_i32_e32 v43, v43
	v_med3_f32 v102, v98, s73, v167
	v_med3_f32 v99, v99, s73, v167
	v_mov_b32_e32 v98, v151
	v_cvt_pk_fp8_f32 v98, v102, v99
	v_med3_f32 v99, v104, s73, v167
	v_med3_f32 v102, v105, s73, v167
	v_pk_mul_f32 v[104:105], v[106:107], s[72:73] op_sel_hi:[1,0]
	v_cvt_pk_fp8_f32 v98, v99, v102 op_sel:[0,0,1]
	v_pk_mul_f32 v[102:103], v[108:109], s[72:73] op_sel_hi:[1,0]
	v_exp_f32_e32 v104, v104
	v_exp_f32_e32 v105, v105
	v_exp_f32_e32 v102, v102
	v_exp_f32_e32 v103, v103
	v_mov_b32_e32 v99, v151
	v_pk_add_f32 v[104:105], v[104:105], 1.0 op_sel_hi:[1,0]
	v_cvt_f32_i32_e32 v42, v42
	v_pk_add_f32 v[102:103], v[102:103], 1.0 op_sel_hi:[1,0]
	v_rcp_f32_e32 v104, v104
	v_rcp_f32_e32 v105, v105
	v_rcp_f32_e32 v102, v102
	v_rcp_f32_e32 v103, v103
	v_cvt_f32_i32_e32 v37, v37
	v_pk_mul_f32 v[104:105], v[106:107], v[104:105]
	v_cvt_f32_i32_e32 v36, v36
	v_pk_mul_f32 v[102:103], v[108:109], v[102:103]
	v_cvt_f32_i32_e32 v35, v35
	v_pk_mul_f32 v[100:101], v[100:101], v[102:103]
	v_pk_mul_f32 v[102:103], v[114:115], v[104:105]
	v_med3_f32 v100, v100, s73, v167
	v_med3_f32 v102, v102, s73, v167
	v_med3_f32 v103, v103, s73, v167
	v_cvt_pk_fp8_f32 v99, v102, v103
	v_med3_f32 v101, v101, s73, v167
	v_pk_mul_f32 v[102:103], v[168:169], v[80:81] op_sel_hi:[0,1]
	v_pk_mul_f32 v[96:97], v[102:103], v[96:97]
	v_cvt_pk_fp8_f32 v99, v100, v101 op_sel:[0,0,1]
	v_mul_f32_e32 v100, 0x41000000, v168
	v_pk_mul_f32 v[102:103], v[168:169], v[76:77] op_sel_hi:[0,1]
	v_pk_mul_f32 v[104:105], v[168:169], v[78:79] op_sel_hi:[0,1]
	v_pk_mul_f32 v[92:93], v[102:103], v[92:93]
	v_pk_mul_f32 v[102:103], v[100:101], v[72:73] op_sel_hi:[0,1]
	v_pk_mul_f32 v[94:95], v[104:105], v[94:95]
	v_pk_mul_f32 v[104:105], v[168:169], v[74:75] op_sel_hi:[0,1]
	v_pk_mul_f32 v[88:89], v[102:103], v[88:89]
	v_pk_mul_f32 v[102:103], v[100:101], v[68:69] op_sel_hi:[0,1]
	v_pk_mul_f32 v[90:91], v[104:105], v[90:91]
	v_pk_mul_f32 v[104:105], v[100:101], v[70:71] op_sel_hi:[0,1]
	v_pk_mul_f32 v[100:101], v[100:101], v[66:67] op_sel_hi:[0,1]
	v_pk_mul_f32 v[84:85], v[102:103], v[84:85]
	v_pk_mul_f32 v[102:103], v[94:95], s[72:73] op_sel_hi:[1,0]
	v_pk_mul_f32 v[82:83], v[100:101], v[82:83]
	v_pk_mul_f32 v[100:101], v[96:97], s[72:73] op_sel_hi:[1,0]
	v_exp_f32_e32 v102, v102
	v_exp_f32_e32 v103, v103
	v_exp_f32_e32 v100, v100
	v_exp_f32_e32 v101, v101
	v_pk_mul_f32 v[86:87], v[104:105], v[86:87]
	v_pk_add_f32 v[102:103], v[102:103], 1.0 op_sel_hi:[1,0]
	v_cvt_f32_i32_e32 v34, v34
	v_pk_add_f32 v[100:101], v[100:101], 1.0 op_sel_hi:[1,0]
	v_rcp_f32_e32 v102, v102
	v_rcp_f32_e32 v103, v103
	v_rcp_f32_e32 v100, v100
	v_rcp_f32_e32 v101, v101
	v_cvt_f32_i32_e32 v39, v39
	v_pk_mul_f32 v[94:95], v[94:95], v[102:103]
	v_cvt_f32_i32_e32 v38, v38
	v_pk_mul_f32 v[96:97], v[96:97], v[100:101]
	v_pk_mul_f32 v[86:87], v[86:87], v[94:95]
	v_pk_mul_f32 v[88:89], v[88:89], v[96:97]
	v_med3_f32 v86, v86, s73, v167
	v_med3_f32 v87, v87, s73, v167
	v_mov_b32_e32 v100, v151
	v_cvt_pk_fp8_f32 v100, v86, v87
	v_med3_f32 v86, v88, s73, v167
	v_med3_f32 v87, v89, s73, v167
	v_pk_mul_f32 v[88:89], v[90:91], s[72:73] op_sel_hi:[1,0]
	v_cvt_pk_fp8_f32 v100, v86, v87 op_sel:[0,0,1]
	v_exp_f32_e32 v88, v88
	v_exp_f32_e32 v89, v89
	v_pk_mul_f32 v[86:87], v[92:93], s[72:73] op_sel_hi:[1,0]
	v_mov_b32_e32 v101, v151
	v_exp_f32_e32 v86, v86
	v_exp_f32_e32 v87, v87
	v_pk_add_f32 v[88:89], v[88:89], 1.0 op_sel_hi:[1,0]
	v_permlane16_swap_b32_e32 v98, v100
	v_rcp_f32_e32 v88, v88
	v_rcp_f32_e32 v89, v89
	v_pk_add_f32 v[86:87], v[86:87], 1.0 op_sel_hi:[1,0]
	v_cvt_f32_i32_e32 v33, v33
	v_rcp_f32_e32 v86, v86
	v_rcp_f32_e32 v87, v87
	v_pk_mul_f32 v[88:89], v[90:91], v[88:89]
	v_cvt_f32_i32_e32 v32, v32
	v_pk_mul_f32 v[82:83], v[82:83], v[88:89]
	v_pk_mul_f32 v[86:87], v[92:93], v[86:87]
	v_med3_f32 v82, v82, s73, v167
	v_med3_f32 v83, v83, s73, v167
	v_cvt_pk_fp8_f32 v101, v82, v83
	v_pk_mul_f32 v[84:85], v[84:85], v[86:87]
	v_pk_mul_f32 v[86:87], v[166:167], v[78:79] op_sel_hi:[0,1]
	v_med3_f32 v82, v84, s73, v167
	v_med3_f32 v83, v85, s73, v167
	v_cvt_pk_fp8_f32 v101, v82, v83 op_sel:[0,0,1]
	v_add_co_u32_e32 v82, vcc, s34, v158
	v_pk_mul_f32 v[84:85], v[166:167], v[80:81] op_sel_hi:[0,1]
	v_permlane16_swap_b32_e32 v99, v101
	v_addc_co_u32_e32 v83, vcc, 0, v159, vcc
	global_store_dwordx4 v[82:83], v[98:101], off
	v_mul_f32_e32 v82, 0x41000000, v166
	v_pk_mul_f32 v[64:65], v[84:85], v[64:65]
	v_pk_mul_f32 v[84:85], v[166:167], v[76:77] op_sel_hi:[0,1]
	v_pk_mul_f32 v[62:63], v[86:87], v[62:63]
	v_pk_mul_f32 v[86:87], v[166:167], v[74:75] op_sel_hi:[0,1]
	v_pk_mul_f32 v[60:61], v[84:85], v[60:61]
	v_pk_mul_f32 v[84:85], v[82:83], v[72:73] op_sel_hi:[0,1]
	v_pk_mul_f32 v[58:59], v[86:87], v[58:59]
	v_pk_mul_f32 v[86:87], v[82:83], v[70:71] op_sel_hi:[0,1]
	v_pk_mul_f32 v[56:57], v[84:85], v[56:57]
	v_pk_mul_f32 v[84:85], v[82:83], v[68:69] op_sel_hi:[0,1]
	v_pk_mul_f32 v[82:83], v[82:83], v[66:67] op_sel_hi:[0,1]
	v_pk_mul_f32 v[82:83], v[82:83], v[50:51]
	v_pk_mul_f32 v[52:53], v[84:85], v[52:53]
	v_pk_mul_f32 v[50:51], v[64:65], s[72:73] op_sel_hi:[1,0]
	v_pk_mul_f32 v[84:85], v[62:63], s[72:73] op_sel_hi:[1,0]
	v_exp_f32_e32 v50, v50
	v_exp_f32_e32 v84, v84
	v_exp_f32_e32 v85, v85
	v_exp_f32_e32 v51, v51
	v_pk_mul_f32 v[54:55], v[86:87], v[54:55]
	s_mov_b32 s34, 0x58000
	v_pk_add_f32 v[84:85], v[84:85], 1.0 op_sel_hi:[1,0]
	v_pk_add_f32 v[50:51], v[50:51], 1.0 op_sel_hi:[1,0]
	v_rcp_f32_e32 v84, v84
	v_rcp_f32_e32 v85, v85
	v_rcp_f32_e32 v50, v50
	v_rcp_f32_e32 v51, v51
	v_cvt_f32_i32_e32 v31, v31
	v_pk_mul_f32 v[62:63], v[62:63], v[84:85]
	v_cvt_f32_i32_e32 v30, v30
	v_pk_mul_f32 v[50:51], v[64:65], v[50:51]
	v_cvt_f32_i32_e32 v29, v29
	v_pk_mul_f32 v[56:57], v[56:57], v[50:51]
	v_pk_mul_f32 v[50:51], v[54:55], v[62:63]
	v_cvt_f32_i32_e32 v28, v28
	v_med3_f32 v54, v50, s73, v167
	v_med3_f32 v51, v51, s73, v167
	v_mov_b32_e32 v50, v151
	v_cvt_pk_fp8_f32 v50, v54, v51
	v_med3_f32 v51, v56, s73, v167
	v_med3_f32 v54, v57, s73, v167
	v_pk_mul_f32 v[56:57], v[58:59], s[72:73] op_sel_hi:[1,0]
	v_cvt_pk_fp8_f32 v50, v51, v54 op_sel:[0,0,1]
	v_pk_mul_f32 v[54:55], v[60:61], s[72:73] op_sel_hi:[1,0]
	v_exp_f32_e32 v56, v56
	v_exp_f32_e32 v57, v57
	v_exp_f32_e32 v54, v54
	v_exp_f32_e32 v55, v55
	v_mov_b32_e32 v51, v151
	v_pk_add_f32 v[56:57], v[56:57], 1.0 op_sel_hi:[1,0]
	v_cvt_f32_i32_e32 v27, v27
	v_pk_add_f32 v[54:55], v[54:55], 1.0 op_sel_hi:[1,0]
	v_rcp_f32_e32 v56, v56
	v_rcp_f32_e32 v57, v57
	v_rcp_f32_e32 v54, v54
	v_rcp_f32_e32 v55, v55
	v_cvt_f32_i32_e32 v26, v26
	v_pk_mul_f32 v[56:57], v[58:59], v[56:57]
	v_cvt_f32_i32_e32 v25, v25
	v_pk_mul_f32 v[54:55], v[60:61], v[54:55]
	v_cvt_f32_i32_e32 v24, v24
	v_pk_mul_f32 v[52:53], v[52:53], v[54:55]
	v_pk_mul_f32 v[54:55], v[82:83], v[56:57]
	v_med3_f32 v52, v52, s73, v167
	v_med3_f32 v54, v54, s73, v167
	v_med3_f32 v55, v55, s73, v167
	v_cvt_pk_fp8_f32 v51, v54, v55
	v_med3_f32 v53, v53, s73, v167
	v_pk_mul_f32 v[54:55], v[164:165], v[80:81] op_sel_hi:[0,1]
	v_pk_mul_f32 v[48:49], v[54:55], v[48:49]
	v_cvt_pk_fp8_f32 v51, v52, v53 op_sel:[0,0,1]
	v_mul_f32_e32 v52, 0x41000000, v164
	v_pk_mul_f32 v[54:55], v[164:165], v[76:77] op_sel_hi:[0,1]
	v_pk_mul_f32 v[56:57], v[164:165], v[78:79] op_sel_hi:[0,1]
	v_pk_mul_f32 v[44:45], v[54:55], v[44:45]
	v_pk_mul_f32 v[54:55], v[52:53], v[72:73] op_sel_hi:[0,1]
	v_pk_mul_f32 v[46:47], v[56:57], v[46:47]
	v_pk_mul_f32 v[56:57], v[164:165], v[74:75] op_sel_hi:[0,1]
	v_pk_mul_f32 v[40:41], v[54:55], v[40:41]
	v_pk_mul_f32 v[54:55], v[52:53], v[68:69] op_sel_hi:[0,1]
	v_pk_mul_f32 v[42:43], v[56:57], v[42:43]
	v_pk_mul_f32 v[56:57], v[52:53], v[70:71] op_sel_hi:[0,1]
	v_pk_mul_f32 v[52:53], v[52:53], v[66:67] op_sel_hi:[0,1]
	v_pk_mul_f32 v[36:37], v[54:55], v[36:37]
	v_pk_mul_f32 v[54:55], v[46:47], s[72:73] op_sel_hi:[1,0]
	v_pk_mul_f32 v[34:35], v[52:53], v[34:35]
	v_pk_mul_f32 v[52:53], v[48:49], s[72:73] op_sel_hi:[1,0]
	v_exp_f32_e32 v54, v54
	v_exp_f32_e32 v55, v55
	v_exp_f32_e32 v52, v52
	v_exp_f32_e32 v53, v53
	v_pk_mul_f32 v[38:39], v[56:57], v[38:39]
	v_pk_add_f32 v[54:55], v[54:55], 1.0 op_sel_hi:[1,0]
	v_cvt_f32_i32_e32 v21, v21
	v_pk_add_f32 v[52:53], v[52:53], 1.0 op_sel_hi:[1,0]
	v_rcp_f32_e32 v54, v54
	v_rcp_f32_e32 v55, v55
	v_rcp_f32_e32 v52, v52
	v_rcp_f32_e32 v53, v53
	v_cvt_f32_i32_e32 v20, v20
	v_pk_mul_f32 v[46:47], v[46:47], v[54:55]
	v_cvt_f32_i32_e32 v19, v19
	v_pk_mul_f32 v[48:49], v[48:49], v[52:53]
	v_pk_mul_f32 v[38:39], v[38:39], v[46:47]
	v_pk_mul_f32 v[40:41], v[40:41], v[48:49]
	v_med3_f32 v38, v38, s73, v167
	v_med3_f32 v39, v39, s73, v167
	v_mov_b32_e32 v52, v151
	v_cvt_pk_fp8_f32 v52, v38, v39
	v_med3_f32 v38, v40, s73, v167
	v_med3_f32 v39, v41, s73, v167
	v_pk_mul_f32 v[40:41], v[42:43], s[72:73] op_sel_hi:[1,0]
	v_cvt_pk_fp8_f32 v52, v38, v39 op_sel:[0,0,1]
	v_exp_f32_e32 v40, v40
	v_exp_f32_e32 v41, v41
	v_pk_mul_f32 v[38:39], v[44:45], s[72:73] op_sel_hi:[1,0]
	v_mov_b32_e32 v53, v151
	v_exp_f32_e32 v38, v38
	v_exp_f32_e32 v39, v39
	v_pk_add_f32 v[40:41], v[40:41], 1.0 op_sel_hi:[1,0]
	v_permlane16_swap_b32_e32 v50, v52
	v_rcp_f32_e32 v40, v40
	v_rcp_f32_e32 v41, v41
	v_pk_add_f32 v[38:39], v[38:39], 1.0 op_sel_hi:[1,0]
	v_cvt_f32_i32_e32 v18, v18
	v_rcp_f32_e32 v38, v38
	v_rcp_f32_e32 v39, v39
	v_pk_mul_f32 v[40:41], v[42:43], v[40:41]
	v_cvt_f32_i32_e32 v23, v23
	v_pk_mul_f32 v[34:35], v[34:35], v[40:41]
	v_pk_mul_f32 v[38:39], v[44:45], v[38:39]
	v_med3_f32 v34, v34, s73, v167
	v_med3_f32 v35, v35, s73, v167
	v_cvt_pk_fp8_f32 v53, v34, v35
	v_pk_mul_f32 v[36:37], v[36:37], v[38:39]
	v_pk_mul_f32 v[38:39], v[162:163], v[78:79] op_sel_hi:[0,1]
	v_med3_f32 v34, v36, s73, v167
	v_med3_f32 v35, v37, s73, v167
	v_cvt_pk_fp8_f32 v53, v34, v35 op_sel:[0,0,1]
	v_add_co_u32_e32 v34, vcc, s34, v158
	v_pk_mul_f32 v[36:37], v[162:163], v[80:81] op_sel_hi:[0,1]
	v_permlane16_swap_b32_e32 v51, v53
	v_addc_co_u32_e32 v35, vcc, 0, v159, vcc
	global_store_dwordx4 v[34:35], v[50:53], off
	v_mul_f32_e32 v34, 0x41000000, v162
	v_pk_mul_f32 v[32:33], v[36:37], v[32:33]
	v_pk_mul_f32 v[36:37], v[162:163], v[76:77] op_sel_hi:[0,1]
	v_pk_mul_f32 v[30:31], v[38:39], v[30:31]
	v_pk_mul_f32 v[38:39], v[162:163], v[74:75] op_sel_hi:[0,1]
	v_pk_mul_f32 v[28:29], v[36:37], v[28:29]
	v_pk_mul_f32 v[36:37], v[34:35], v[72:73] op_sel_hi:[0,1]
	v_pk_mul_f32 v[26:27], v[38:39], v[26:27]
	v_pk_mul_f32 v[38:39], v[34:35], v[70:71] op_sel_hi:[0,1]
	v_pk_mul_f32 v[24:25], v[36:37], v[24:25]
	v_pk_mul_f32 v[36:37], v[34:35], v[68:69] op_sel_hi:[0,1]
	v_pk_mul_f32 v[34:35], v[34:35], v[66:67] op_sel_hi:[0,1]
	v_pk_mul_f32 v[34:35], v[34:35], v[18:19]
	v_pk_mul_f32 v[20:21], v[36:37], v[20:21]
	v_pk_mul_f32 v[18:19], v[32:33], s[72:73] op_sel_hi:[1,0]
	v_pk_mul_f32 v[36:37], v[30:31], s[72:73] op_sel_hi:[1,0]
	v_exp_f32_e32 v18, v18
	v_exp_f32_e32 v36, v36
	v_exp_f32_e32 v37, v37
	v_exp_f32_e32 v19, v19
	v_cvt_f32_i32_e32 v22, v22
	v_cvt_f32_i32_e32 v17, v17
	v_pk_add_f32 v[36:37], v[36:37], 1.0 op_sel_hi:[1,0]
	v_pk_add_f32 v[18:19], v[18:19], 1.0 op_sel_hi:[1,0]
	v_rcp_f32_e32 v36, v36
	v_rcp_f32_e32 v37, v37
	v_rcp_f32_e32 v18, v18
	v_rcp_f32_e32 v19, v19
	v_pk_mul_f32 v[22:23], v[38:39], v[22:23]
	v_pk_mul_f32 v[30:31], v[30:31], v[36:37]
	v_cvt_f32_i32_e32 v16, v16
	v_pk_mul_f32 v[18:19], v[32:33], v[18:19]
	v_cvt_f32_i32_e32 v13, v13
	v_pk_mul_f32 v[24:25], v[24:25], v[18:19]
	v_pk_mul_f32 v[18:19], v[22:23], v[30:31]
	v_cvt_f32_i32_e32 v12, v12
	v_med3_f32 v22, v18, s73, v167
	v_med3_f32 v19, v19, s73, v167
	v_mov_b32_e32 v18, v151
	v_cvt_pk_fp8_f32 v18, v22, v19
	v_med3_f32 v19, v24, s73, v167
	v_med3_f32 v22, v25, s73, v167
	v_pk_mul_f32 v[24:25], v[26:27], s[72:73] op_sel_hi:[1,0]
	v_cvt_pk_fp8_f32 v18, v19, v22 op_sel:[0,0,1]
	v_pk_mul_f32 v[22:23], v[28:29], s[72:73] op_sel_hi:[1,0]
	v_exp_f32_e32 v24, v24
	v_exp_f32_e32 v25, v25
	v_exp_f32_e32 v22, v22
	v_exp_f32_e32 v23, v23
	v_mov_b32_e32 v19, v151
	v_pk_add_f32 v[24:25], v[24:25], 1.0 op_sel_hi:[1,0]
	v_cvt_f32_i32_e32 v15, v15
	v_pk_add_f32 v[22:23], v[22:23], 1.0 op_sel_hi:[1,0]
	v_rcp_f32_e32 v24, v24
	v_rcp_f32_e32 v25, v25
	v_rcp_f32_e32 v22, v22
	v_rcp_f32_e32 v23, v23
	v_cvt_f32_i32_e32 v14, v14
	v_pk_mul_f32 v[24:25], v[26:27], v[24:25]
	v_cvt_f32_i32_e32 v9, v9
	v_pk_mul_f32 v[22:23], v[28:29], v[22:23]
	v_cvt_f32_i32_e32 v8, v8
	v_pk_mul_f32 v[20:21], v[20:21], v[22:23]
	v_pk_mul_f32 v[22:23], v[34:35], v[24:25]
	v_med3_f32 v20, v20, s73, v167
	v_med3_f32 v22, v22, s73, v167
	v_med3_f32 v23, v23, s73, v167
	v_cvt_pk_fp8_f32 v19, v22, v23
	v_med3_f32 v21, v21, s73, v167
	v_pk_mul_f32 v[22:23], v[80:81], v[160:161] op_sel_hi:[1,0]
	v_cvt_f32_i32_e32 v11, v11
	v_cvt_f32_i32_e32 v10, v10
	v_cvt_f32_i32_e32 v5, v5
	v_cvt_f32_i32_e32 v4, v4
	v_cvt_pk_fp8_f32 v19, v20, v21 op_sel:[0,0,1]
	v_mul_f32_e32 v20, 0x41000000, v160
	v_pk_mul_f32 v[16:17], v[22:23], v[16:17]
	v_pk_mul_f32 v[22:23], v[160:161], v[76:77] op_sel_hi:[0,1]
	v_cvt_f32_i32_e32 v3, v3
	v_cvt_f32_i32_e32 v2, v2
	v_pk_mul_f32 v[24:25], v[78:79], v[160:161] op_sel_hi:[1,0]
	v_pk_mul_f32 v[12:13], v[22:23], v[12:13]
	v_pk_mul_f32 v[22:23], v[20:21], v[72:73] op_sel_hi:[0,1]
	v_pk_mul_f32 v[14:15], v[24:25], v[14:15]
	v_pk_mul_f32 v[24:25], v[160:161], v[74:75] op_sel_hi:[0,1]
	v_pk_mul_f32 v[8:9], v[22:23], v[8:9]
	v_pk_mul_f32 v[22:23], v[20:21], v[68:69] op_sel_hi:[0,1]
	v_pk_mul_f32 v[10:11], v[24:25], v[10:11]
	v_pk_mul_f32 v[24:25], v[20:21], v[70:71] op_sel_hi:[0,1]
	v_pk_mul_f32 v[20:21], v[20:21], v[66:67] op_sel_hi:[0,1]
	v_pk_mul_f32 v[4:5], v[22:23], v[4:5]
	v_pk_mul_f32 v[22:23], v[14:15], s[72:73] op_sel_hi:[1,0]
	v_pk_mul_f32 v[2:3], v[20:21], v[2:3]
	v_pk_mul_f32 v[20:21], v[16:17], s[72:73] op_sel_hi:[1,0]
	v_exp_f32_e32 v22, v22
	v_exp_f32_e32 v23, v23
	v_exp_f32_e32 v20, v20
	v_exp_f32_e32 v21, v21
	v_cvt_f32_i32_e32 v7, v7
	v_pk_add_f32 v[22:23], v[22:23], 1.0 op_sel_hi:[1,0]
	v_cvt_f32_i32_e32 v6, v6
	v_pk_add_f32 v[20:21], v[20:21], 1.0 op_sel_hi:[1,0]
	v_rcp_f32_e32 v22, v22
	v_rcp_f32_e32 v23, v23
	v_rcp_f32_e32 v20, v20
	v_rcp_f32_e32 v21, v21
	v_pk_mul_f32 v[6:7], v[24:25], v[6:7]
	v_pk_mul_f32 v[14:15], v[14:15], v[22:23]
	v_permlane16_swap_b32_e32 v130, v132
	v_pk_mul_f32 v[16:17], v[16:17], v[20:21]
	v_pk_mul_f32 v[6:7], v[6:7], v[14:15]
	v_pk_mul_f32 v[8:9], v[8:9], v[16:17]
	v_med3_f32 v6, v6, s73, v167
	v_med3_f32 v7, v7, s73, v167
	v_mov_b32_e32 v20, v151
	v_cvt_pk_fp8_f32 v20, v6, v7
	v_med3_f32 v6, v8, s73, v167
	v_med3_f32 v7, v9, s73, v167
	v_pk_mul_f32 v[8:9], v[10:11], s[72:73] op_sel_hi:[1,0]
	v_cvt_pk_fp8_f32 v20, v6, v7 op_sel:[0,0,1]
	v_exp_f32_e32 v8, v8
	v_exp_f32_e32 v9, v9
	v_pk_mul_f32 v[6:7], v[12:13], s[72:73] op_sel_hi:[1,0]
	v_mov_b32_e32 v21, v151
	v_exp_f32_e32 v6, v6
	v_exp_f32_e32 v7, v7
	v_pk_add_f32 v[8:9], v[8:9], 1.0 op_sel_hi:[1,0]
	v_permlane16_swap_b32_e32 v131, v133
	v_rcp_f32_e32 v8, v8
	v_rcp_f32_e32 v9, v9
	v_pk_add_f32 v[6:7], v[6:7], 1.0 op_sel_hi:[1,0]
	v_permlane16_swap_b32_e32 v18, v20
	v_rcp_f32_e32 v6, v6
	v_rcp_f32_e32 v7, v7
	v_pk_mul_f32 v[8:9], v[10:11], v[8:9]
	s_mov_b64 s[34:35], -1
	v_pk_mul_f32 v[2:3], v[2:3], v[8:9]
	v_pk_mul_f32 v[6:7], v[12:13], v[6:7]
	v_med3_f32 v2, v2, s73, v167
	v_med3_f32 v3, v3, s73, v167
	v_cvt_pk_fp8_f32 v21, v2, v3
	v_pk_mul_f32 v[4:5], v[4:5], v[6:7]
	global_store_dwordx4 v[158:159], v[130:133], off
	v_med3_f32 v2, v4, s73, v167
	v_med3_f32 v3, v5, s73, v167
	v_cvt_pk_fp8_f32 v21, v2, v3 op_sel:[0,0,1]
	v_add_co_u32_e32 v2, vcc, 0x6e000, v158
	s_nop 0
	v_permlane16_swap_b32_e32 v19, v21
	v_addc_co_u32_e32 v3, vcc, 0, v159, vcc
	s_andn2_b64 vcc, exec, s[2:3]
	global_store_dwordx4 v[2:3], v[18:21], off
	s_cbranch_vccnz .LBB0_210
	s_andn2_b64 vcc, exec, s[14:15]
	s_cbranch_vccnz .LBB0_209
	s_barrier
	s_branch .LBB0_209

.Llb_loc_s2:
	s_and_saveexec_b64 s[0:1], vcc
	s_cbranch_execz .Llb_done_s2
	v_mov_b32_e32 v1, s88
	ds_read_b32 v2, v1
	v_readlane_b32 s4, v254, 14
	v_readlane_b32 s10, v254, 12
	v_readlane_b32 s11, v254, 13
	s_lshl_b32 s4, s4, 8
	s_add_u32 s4, s10, s4
	s_addc_u32 s5, s11, 0
	v_mov_b32_e32 v3, 0x2400
	v_mov_b32_e32 v4, 1
	global_atomic_add v3, v4, s[4:5]
	s_waitcnt lgkmcnt(0)
	v_mul_lo_u32 v2, v2, 2
	s_mov_b32 s99, 0

.Llb_loc_s3:
	s_and_saveexec_b64 s[2:3], vcc
	s_cbranch_execz .Llb_done_s3
	v_mov_b32_e32 v1, s88
	ds_read_b32 v2, v1
	v_readlane_b32 s4, v254, 14
	v_readlane_b32 s10, v254, 12
	v_readlane_b32 s11, v254, 13
	s_lshl_b32 s4, s4, 8
	s_add_u32 s4, s10, s4
	s_addc_u32 s5, s11, 0
	v_mov_b32_e32 v3, 0x2400
	v_mov_b32_e32 v4, 1
	global_atomic_add v3, v4, s[4:5]
	v_mov_b32_e32 v5, 0x240c
	global_atomic_add v5, v4, s[10:11]
	s_waitcnt lgkmcnt(0)
	v_mul_lo_u32 v2, v2, 3
	s_mov_b32 s99, 0

.Llb_loc_s4:
	s_and_saveexec_b64 s[2:3], vcc
	s_cbranch_execz .Llb_done_s4
	v_mov_b32_e32 v1, s88
	ds_read_b32 v2, v1
	v_readlane_b32 s4, v254, 14
	v_readlane_b32 s10, v254, 12
	v_readlane_b32 s11, v254, 13
	s_lshl_b32 s4, s4, 8
	s_add_u32 s4, s10, s4
	s_addc_u32 s5, s11, 0
	v_mov_b32_e32 v3, 0x2400
	v_mov_b32_e32 v4, 1
	global_atomic_add v3, v4, s[4:5]
	s_waitcnt lgkmcnt(0)
	v_mul_lo_u32 v2, v2, 4
	s_mov_b32 s99, 0

.Llb_loc_s5:
	s_and_saveexec_b64 s[0:1], vcc
	s_cbranch_execz .Llb_done_s5
	v_mov_b32_e32 v1, s88
	ds_read_b32 v2, v1
	v_readlane_b32 s4, v254, 14
	v_readlane_b32 s10, v254, 12
	v_readlane_b32 s11, v254, 13
	s_lshl_b32 s4, s4, 8
	s_add_u32 s4, s10, s4
	s_addc_u32 s5, s11, 0
	v_mov_b32_e32 v3, 0x2400
	v_mov_b32_e32 v4, 1
	global_atomic_add v3, v4, s[4:5]
	v_mov_b32_e32 v5, 0x2408
	global_atomic_add v5, v4, s[10:11]
	s_waitcnt lgkmcnt(0)
	v_mul_lo_u32 v2, v2, 5
	s_mov_b32 s99, 0

.Llb_loc_s7:
	s_and_saveexec_b64 s[2:3], vcc
	s_cbranch_execz .Llb_done_s7
	v_mov_b32_e32 v1, s88
	ds_read_b32 v2, v1
	v_readlane_b32 s4, v254, 14
	v_readlane_b32 s10, v254, 12
	v_readlane_b32 s11, v254, 13
	s_lshl_b32 s4, s4, 8
	s_add_u32 s4, s10, s4
	s_addc_u32 s5, s11, 0
	v_mov_b32_e32 v3, 0x2400
	v_mov_b32_e32 v4, 1
	global_atomic_add v3, v4, s[4:5]
	s_waitcnt lgkmcnt(0)
	v_mul_lo_u32 v2, v2, 6
	s_mov_b32 s99, 0

.Llb_loc_s8:
	s_and_saveexec_b64 s[0:1], vcc
	s_cbranch_execz .Llb_done_s8
	v_mov_b32_e32 v1, s88
	ds_read_b32 v2, v1
	v_readlane_b32 s4, v254, 14
	v_readlane_b32 s10, v254, 12
	v_readlane_b32 s11, v254, 13
	s_lshl_b32 s4, s4, 8
	s_add_u32 s4, s10, s4
	s_addc_u32 s5, s11, 0
	v_mov_b32_e32 v3, 0x2400
	v_mov_b32_e32 v4, 1
	global_atomic_add v3, v4, s[4:5]
	s_waitcnt lgkmcnt(0)
	v_mul_lo_u32 v2, v2, 7
	s_mov_b32 s99, 0
